# E22 on E23: pool epilogue scale vectors prefetched before MFMA block, per-site vmcnt(0) removed
# baseline (speedup 1.0000x reference)
.LBB0_487:
	s_waitcnt lgkmcnt(0)
	s_or_b64 exec, exec, s[6:7]
	v_lshrrev_b32_e32 v6, 1, v10
	v_and_b32_e32 v6, 0x60, v6
	v_cmp_gt_u32_e32 vcc, s51, v6
	s_barrier
	s_and_saveexec_b64 s[6:7], vcc
	s_cbranch_execz .LBB0_521
	s_lshl_b32 s44, s58, 7
	v_and_b32_e32 v4, 0xffffffc0, v4
	s_lshl_b32 s98, s58, 9
	s_add_u32 s98, s8, s98
	s_addc_u32 s99, s9, 0
	v_or_b32_e32 v66, v4, v216
	v_ashrrev_i32_e32 v67, 31, v66
	v_lshl_add_u64 v[66:67], v[66:67], 2, s[98:99]
	global_load_dwordx4 v[68:71], v[66:67], off
	global_load_dwordx4 v[72:75], v[66:67], off offset:32
	global_load_dwordx4 v[76:79], v[66:67], off offset:64
	global_load_dwordx4 v[80:83], v[66:67], off offset:96
	global_load_dwordx4 v[84:87], v[66:67], off offset:128
	global_load_dwordx4 v[88:91], v[66:67], off offset:160
	global_load_dwordx4 v[92:95], v[66:67], off offset:192
	global_load_dwordx4 v[96:99], v[66:67], off offset:224
	v_add_u32_e32 v42, s44, v4
	v_or_b32_e32 v12, v42, v212
	v_ashrrev_i32_e32 v13, 31, v12
	v_lshlrev_b64 v[8:9], 8, v[12:13]
	v_lshl_add_u64 v[60:61], v[162:163], 0, v[8:9]
	global_load_dwordx4 v[8:11], v[60:61], off
	global_load_dwordx4 v[38:41], v[60:61], off offset:32
	v_or_b32_e32 v12, 32, v12
	v_ashrrev_i32_e32 v13, 31, v12
	v_lshlrev_b64 v[12:13], 8, v[12:13]
	v_lshl_add_u64 v[62:63], v[162:163], 0, v[12:13]
	global_load_dwordx4 v[12:15], v[62:63], off
	v_or_b32_e32 v43, v6, v212
	v_mad_u32_u24 v64, v43, s3, v192
	ds_read_b128 v[16:19], v64 offset:39168
	ds_read_b128 v[44:47], v64 offset:39200
	global_load_dwordx4 v[48:51], v[62:63], off offset:32
	global_load_dwordx4 v[52:55], v[60:61], off offset:64
	v_cmp_gt_u32_e32 vcc, s51, v43
	s_waitcnt vmcnt(4) lgkmcnt(1)
	v_mfma_f32_32x32x16_bf16 v[22:37], v[8:11], v[16:19], 0
	s_waitcnt vmcnt(2)
	v_mfma_f32_32x32x16_bf16 v[6:21], v[12:15], v[16:19], 0
	s_waitcnt lgkmcnt(0)
	v_mfma_f32_32x32x16_bf16 v[22:37], v[38:41], v[44:47], v[22:37]
	global_load_dwordx4 v[38:41], v[62:63], off offset:64
	s_waitcnt vmcnt(2)
	v_mfma_f32_32x32x16_bf16 v[6:21], v[48:51], v[44:47], v[6:21]
	global_load_dwordx4 v[44:47], v[60:61], off offset:96
	ds_read_b128 v[48:51], v64 offset:39232
	ds_read_b128 v[56:59], v64 offset:39264
	s_waitcnt vmcnt(2) lgkmcnt(1)
	v_mfma_f32_32x32x16_bf16 v[22:37], v[52:55], v[48:51], v[22:37]
	global_load_dwordx4 v[52:55], v[62:63], off offset:96
	s_waitcnt vmcnt(2)
	v_mfma_f32_32x32x16_bf16 v[6:21], v[38:41], v[48:51], v[6:21]
	global_load_dwordx4 v[38:41], v[60:61], off offset:128
	global_load_dwordx4 v[48:51], v[60:61], off offset:160
	s_waitcnt vmcnt(3) lgkmcnt(0)
	v_mfma_f32_32x32x16_bf16 v[22:37], v[44:47], v[56:59], v[22:37]
	global_load_dwordx4 v[44:47], v[62:63], off offset:128
	s_waitcnt vmcnt(3)
	v_mfma_f32_32x32x16_bf16 v[6:21], v[52:55], v[56:59], v[6:21]
	ds_read_b128 v[52:55], v64 offset:39296
	ds_read_b128 v[56:59], v64 offset:39328
	s_waitcnt vmcnt(2) lgkmcnt(1)
	v_mfma_f32_32x32x16_bf16 v[22:37], v[38:41], v[52:55], v[22:37]
	global_load_dwordx4 v[38:41], v[62:63], off offset:160
	s_waitcnt vmcnt(1)
	v_mfma_f32_32x32x16_bf16 v[6:21], v[44:47], v[52:55], v[6:21]
	global_load_dwordx4 v[44:47], v[60:61], off offset:192
	s_waitcnt lgkmcnt(0)
	v_mfma_f32_32x32x16_bf16 v[22:37], v[48:51], v[56:59], v[22:37]
	global_load_dwordx4 v[48:51], v[62:63], off offset:192
	s_waitcnt vmcnt(2)
	v_mfma_f32_32x32x16_bf16 v[6:21], v[38:41], v[56:59], v[6:21]
	global_load_dwordx4 v[38:41], v[60:61], off offset:224
	ds_read_b128 v[52:55], v64 offset:39360
	ds_read_b128 v[56:59], v64 offset:39392
	s_waitcnt vmcnt(2) lgkmcnt(1)
	v_mfma_f32_32x32x16_bf16 v[22:37], v[44:47], v[52:55], v[22:37]
	global_load_dwordx4 v[44:47], v[62:63], off offset:224
	s_waitcnt vmcnt(2)
	v_mfma_f32_32x32x16_bf16 v[6:21], v[48:51], v[52:55], v[6:21]
	s_waitcnt vmcnt(1) lgkmcnt(0)
	v_mfma_f32_32x32x16_bf16 v[22:37], v[38:41], v[56:59], v[22:37]
	s_waitcnt vmcnt(0)
	v_mfma_f32_32x32x16_bf16 v[6:21], v[44:47], v[56:59], v[6:21]
	s_and_b64 exec, exec, vcc
	s_cbranch_execz .LBB0_521
	s_add_i32 s45, s49, s50
	s_lshl_b32 s18, s44, 1
	s_lshl_b32 s4, s44, 2
	v_or_b32_e32 v38, v4, v216
	s_add_u32 s4, s8, s4
	s_addc_u32 s5, s9, 0
	v_ashrrev_i32_e32 v39, 31, v38
	v_lshl_add_u64 v[40:41], v[38:39], 2, s[4:5]
	v_cndmask_b32_e64 v48, 0, 1, s[40:41]
	v_add_u32_e32 v4, s45, v43
	v_cmp_ne_u32_e64 s[4:5], 1, v48
	v_lshlrev_b64 v[48:49], 11, v[4:5]
	v_lshl_add_u64 v[48:49], s[24:25], 0, v[48:49]
	v_lshl_add_u64 v[48:49], v[48:49], 0, s[18:19]
	s_mov_b64 s[42:43], -1
	s_andn2_b64 vcc, exec, s[40:41]
	s_waitcnt vmcnt(0)
	v_pk_mul_f32 v[22:23], v[22:23], v[68:69]
	v_pk_mul_f32 v[24:25], v[24:25], v[70:71]
	v_cvt_pk_bf16_f32 v44, v22, v23
	v_cvt_pk_bf16_f32 v45, v24, v25
	v_lshl_add_u64 v[22:23], v[38:39], 1, v[48:49]
	s_cbranch_vccnz .LBB0_491
	s_mov_b64 s[42:43], 0
	global_store_dwordx2 v[22:23], v[44:45], off

.LBB0_493:
	s_and_b64 vcc, exec, s[4:5]
	s_mov_b64 s[40:41], -1
	v_pk_mul_f32 v[26:27], v[26:27], v[72:73]
	v_pk_mul_f32 v[28:29], v[28:29], v[74:75]
	v_cvt_pk_bf16_f32 v26, v26, v27
	v_cvt_pk_bf16_f32 v27, v28, v29
	s_cbranch_vccnz .LBB0_495
	s_mov_b64 s[40:41], 0
	global_store_dwordx2 v[22:23], v[26:27], off offset:16

.LBB0_497:
	s_and_b64 vcc, exec, s[4:5]
	s_mov_b64 s[40:41], -1
	v_pk_mul_f32 v[26:27], v[30:31], v[76:77]
	v_pk_mul_f32 v[28:29], v[32:33], v[78:79]
	v_cvt_pk_bf16_f32 v26, v26, v27
	v_cvt_pk_bf16_f32 v27, v28, v29
	s_cbranch_vccnz .LBB0_499
	s_mov_b64 s[40:41], 0
	global_store_dwordx2 v[22:23], v[26:27], off offset:32

.LBB0_501:
	s_and_b64 vcc, exec, s[4:5]
	s_mov_b64 s[40:41], -1
	v_pk_mul_f32 v[26:27], v[34:35], v[80:81]
	v_pk_mul_f32 v[28:29], v[36:37], v[82:83]
	v_cvt_pk_bf16_f32 v26, v26, v27
	v_cvt_pk_bf16_f32 v27, v28, v29
	s_cbranch_vccnz .LBB0_503
	s_mov_b64 s[40:41], 0
	global_store_dwordx2 v[22:23], v[26:27], off offset:48

.LBB0_505:
	s_and_b64 vcc, exec, s[4:5]
	s_mov_b64 s[40:41], -1
	v_pk_mul_f32 v[6:7], v[6:7], v[84:85]
	v_pk_mul_f32 v[8:9], v[8:9], v[86:87]
	v_cvt_pk_bf16_f32 v6, v6, v7
	v_cvt_pk_bf16_f32 v7, v8, v9
	s_cbranch_vccnz .LBB0_507
	s_mov_b64 s[40:41], 0
	global_store_dwordx2 v[22:23], v[6:7], off offset:64

.LBB0_509:
	s_and_b64 vcc, exec, s[4:5]
	s_mov_b64 s[40:41], -1
	v_pk_mul_f32 v[6:7], v[10:11], v[88:89]
	v_pk_mul_f32 v[8:9], v[12:13], v[90:91]
	v_cvt_pk_bf16_f32 v6, v6, v7
	v_cvt_pk_bf16_f32 v7, v8, v9
	s_cbranch_vccnz .LBB0_511
	s_mov_b64 s[40:41], 0
	global_store_dwordx2 v[22:23], v[6:7], off offset:80

.LBB0_513:
	s_and_b64 vcc, exec, s[4:5]
	s_mov_b64 s[40:41], -1
	v_pk_mul_f32 v[6:7], v[14:15], v[92:93]
	v_pk_mul_f32 v[8:9], v[16:17], v[94:95]
	v_cvt_pk_bf16_f32 v6, v6, v7
	v_cvt_pk_bf16_f32 v7, v8, v9
	s_cbranch_vccnz .LBB0_515
	s_mov_b64 s[40:41], 0
	global_store_dwordx2 v[22:23], v[6:7], off offset:96

.LBB0_517:
	s_and_b64 vcc, exec, s[4:5]
	s_mov_b64 s[4:5], -1
	v_pk_mul_f32 v[6:7], v[18:19], v[96:97]
	v_pk_mul_f32 v[8:9], v[20:21], v[98:99]
	v_cvt_pk_bf16_f32 v6, v6, v7
	v_cvt_pk_bf16_f32 v7, v8, v9
	s_cbranch_vccnz .LBB0_519
	s_mov_b64 s[4:5], 0
	global_store_dwordx2 v[22:23], v[6:7], off offset:112
